# static s_setprio 1 for waves 4-7 during the attention phase (reset to 0 at phase exit)
# speedup vs baseline: 1.0012x; 1.0012x over previous
; __device__ __forceinline__ unsigned char* arg_ws(const Frame& F) { return (unsigned char*)arg_in(F, AW_WS / 2); }
; #define FRESH() Frame Fp = F; { int t_ = HW_TID(); asm volatile("" : "+v"(t_)); Fp.tid = t_; Fp.lane = t_ & 63; Fp.wave = __builtin_amdgcn_readfirstlane(t_ >> 6); int v_ = F.vcu; asm volatile("" : "+s"(v_)); Fp.vcu = v_; Fp.gw = v_ * NWAVES + Fp.wave; int z_ = 0; asm volatile("" : "+v"(z_)); Fp.zero = z_; }
; #define OBP(off) (arg_out(Fp) + (off))
; __device__ __forceinline__ void attn_phase(const Frame& F, const bf16_t* Q, const bf16_t* KN, const bf16_t* KR, const bf16_t* V, bf16_t* O) {
;     constexpr int NQP = (LP_P + 255) / 256, NQS = (LP_S + 255) / 256, NUP = NP * MH * NQP  , NUS = NS * MH * NQS  ;
;     const int c = F.vcu; const bool exact = (F.G == 256);
;     const int np = exact ? (c < 64 ? 9 : 8) : (NUP - c + F.G - 1) / F.G, ns = exact ? (c < 64 ? 7 : 9) : 0;
;     const int ntot = exact ? np + ns : (NUP + NUS - c + F.G - 1) / F.G;
;     for (int i = 0; i < ntot; ++i) {
; __global__ void __launch_bounds__(NWAVES * 64, 2) mk_fwd(Args args) {
;     ...
;             if (PH_ON && EN_ATTN) { FRESH(); unsigned char* ws = arg_ws(Fp);
;                 for (int rp = 0; rp < REP_ATTN; ++rp) mattn::attn_phase(Fp, (const bf16_t*)(ws + WS_S + S_MQ), (const bf16_t*)(ws + WS_S + S_MKN), (const bf16_t*)OBP(O_MKR), (const bf16_t*)OBP(O_MV), (bf16_t*)(ws + WS_A + X_MO)); }
.LBB0_608:
	v_readlane_b32 s100, v254, 5
	s_cmp_lt_u32 s100, 0x100
	s_cbranch_scc1 .Lattn_prio_skip
	s_setprio 1

; __device__ __forceinline__ unsigned xb_ld(unsigned* p)              { return __hip_atomic_load(p, __ATOMIC_RELAXED, __HIP_MEMORY_SCOPE_AGENT); }
; __device__ __forceinline__ unsigned xb_add(unsigned* p, unsigned v) { return __hip_atomic_fetch_add(p, v, __ATOMIC_RELAXED, __HIP_MEMORY_SCOPE_AGENT); }
; #define XB_SPIN(cond, bar) do { unsigned _sp = 0; while (cond) { __builtin_amdgcn_s_sleep(1); \
;     if ((++_sp & 255u) == 0u) { if (xb_ld(&(bar)[XB_TMO])) break; if (_sp > XB_SPIN_CAP) { atomicAdd(&(bar)[XB_TMO], 1u); break; } } } } while (0)
; __device__ __forceinline__ void xcd_barrier(const XcdBarrier& b, const bool is_t0  ) {
;     asm volatile("s_waitcnt vmcnt(0)" ::: "memory");
;     __syncthreads();
;     if (is_t0) {
;         unsigned* bar = b.bar;
;         __builtin_amdgcn_s_waitcnt(0);
;         unsigned nloc = b.st[0], nx = b.st[1];
;         if (nloc == 0u) { xcd_barrier_complete(bar, b.x, nloc, nx); b.st[0] = nloc; b.st[1] = nx; }
;         const unsigned old = xb_add(&bar[XB_XSUB(b.x)], 1u);
;         const unsigned gen = old / nloc;
;         if (old + 1u == (gen + 1u) * nloc) {
;             __builtin_amdgcn_fence(__ATOMIC_RELEASE, "agent");
;             asm volatile("s_waitcnt vmcnt(0)" ::: "memory");
;             const unsigned og = xb_add(&bar[XB_TOP], 1u);
;             const unsigned tg = og / nx;
;             if (og + 1u == (tg + 1u) * nx) xb_add(&bar[XB_TOPGEN], 1u);
;             else XB_SPIN(xb_ld(&bar[XB_TOPGEN]) == tg, bar);
;             __builtin_amdgcn_fence(__ATOMIC_ACQUIRE, "agent");
;             xb_add(&bar[XB_XGEN(b.x)], 1u);
;             asm volatile("s_waitcnt vmcnt(0)" ::: "memory");
;         } else {
;             XB_SPIN(xb_ld(&bar[XB_XGEN(b.x)]) == gen, bar);
;             __builtin_amdgcn_fence(__ATOMIC_ACQUIRE, "agent");
;             asm volatile("s_waitcnt vmcnt(0)" ::: "memory");
;         }
;     }
;     __syncthreads();
; }
.LBB0_673:
	s_setprio 0
	v_readlane_b32 s0, v255, 24
	s_add_i32 s10, s0, 5
	v_readlane_b32 s0, v254, 3
	v_readlane_b32 s1, v254, 4
	s_cmp_lt_i32 s10, s1
	s_cselect_b64 s[22:23], -1, 0
	s_and_b64 s[0:1], s[28:29], s[22:23]
	s_andn2_b64 vcc, exec, s[0:1]
	s_cbranch_vccnz .LBB0_727
	s_mov_b32 s0, -1
	s_waitcnt vmcnt(0)
	s_waitcnt vmcnt(0) lgkmcnt(0)
	v_mbcnt_lo_u32_b32 v0, s0, 0
	v_mbcnt_hi_u32_b32 v0, s0, v0
	v_sub_u32_e32 v0, 0, v0
	v_readlane_b32 s0, v254, 5
	s_barrier
	s_nop 0
	v_cmp_eq_u32_e32 vcc, s0, v0
	s_and_saveexec_b64 s[0:1], vcc
	s_cbranch_execz .LBB0_726
	v_readlane_b32 s11, v255, 21
	s_waitcnt vmcnt(0) expcnt(0) lgkmcnt(0)
	s_nop 0
	v_mov_b32_e32 v0, s11
	ds_read_b32 v2, v0
	v_readlane_b32 s11, v255, 22
	s_waitcnt lgkmcnt(0)
	v_cmp_ne_u32_e32 vcc, 0, v2
	v_mov_b32_e32 v0, s11
	ds_read_b32 v0, v0
	s_cbranch_vccnz .LBB0_690
	v_readlane_b32 s28, v254, 0
	v_readlane_b32 s29, v254, 1
	s_load_dwordx2 s[12:13], s[28:29], 0x4
	s_waitcnt lgkmcnt(0)
	s_mul_i32 s11, s12, s16
	s_mul_i32 s11, s11, s13
	s_mov_b32 s12, 1
	s_branch .LBB0_678

; #define LAS __attribute__((address_space(3)))
; __global__ void __launch_bounds__(NWAVES * 64, 2) mk_fwd(Args args) {
;     extern __shared__ __attribute__((aligned(16))) unsigned char lds[];
;     Frame F;
;     F.lds = (LAS unsigned char*)lds; F.ldsg = (char*)lds;
;     F.tid = threadIdx.x; F.lane = F.tid & 63; F.wave = __builtin_amdgcn_readfirstlane(F.tid >> 6); const int wave0 = F.wave;
;     F.G = gridDim.x; { const int bx = blockIdx.x; F.vcu = (F.G % 8 == 0) ? (bx % 8) * (F.G / 8) + bx / 8 : bx; }
;     F.gw = F.vcu * NWAVES + F.wave; F.NGW = F.G * NWAVES; { int z_ = 0; asm volatile("" : "+v"(z_)); F.zero = z_; }
;     volatile LAS unsigned* MISC = (volatile LAS unsigned*)(F.lds + MISC_OFF);
;     if (F.tid < 64) MISC[F.tid] = 0u;
;     { const __attribute__((address_space(4))) unsigned* kp = (const __attribute__((address_space(4))) unsigned*)__builtin_amdgcn_kernarg_segment_ptr();
;       if (F.tid < (int)(sizeof(Args) / 4)) ((LAS unsigned*)(F.lds + ARGS_OFF))[F.tid] = kp[F.tid]; }
;     __syncthreads();
	.amdhsa_kernel _Z6mk_fwd4Args
		.amdhsa_group_segment_fixed_size 0
		.amdhsa_private_segment_fixed_size 0
		.amdhsa_kernarg_size 1144
		.amdhsa_user_sgpr_count 2
		.amdhsa_user_sgpr_dispatch_ptr 0
		.amdhsa_user_sgpr_queue_ptr 0
		.amdhsa_user_sgpr_kernarg_segment_ptr 1
		.amdhsa_user_sgpr_dispatch_id 0
		.amdhsa_user_sgpr_kernarg_preload_length 0
		.amdhsa_user_sgpr_kernarg_preload_offset 0
		.amdhsa_user_sgpr_private_segment_size 0
		.amdhsa_uses_dynamic_stack 0
		.amdhsa_enable_private_segment 0
		.amdhsa_system_sgpr_workgroup_id_x 1
		.amdhsa_system_sgpr_workgroup_id_y 0
		.amdhsa_system_sgpr_workgroup_id_z 0
		.amdhsa_system_sgpr_workgroup_info 0
		.amdhsa_system_vgpr_workitem_id 0
		.amdhsa_next_free_vgpr 256
		.amdhsa_next_free_sgpr 102
		.amdhsa_accum_offset 256
		.amdhsa_reserve_vcc 1
		.amdhsa_float_round_mode_32 0
		.amdhsa_float_round_mode_16_64 0
		.amdhsa_float_denorm_mode_32 3
		.amdhsa_float_denorm_mode_16_64 3
		.amdhsa_dx10_clamp 1
		.amdhsa_ieee_mode 1
		.amdhsa_fp16_overflow 0
		.amdhsa_tg_split 0
		.amdhsa_exception_fp_ieee_invalid_op 0
		.amdhsa_exception_fp_denorm_src 0
		.amdhsa_exception_fp_ieee_div_zero 0
		.amdhsa_exception_fp_ieee_overflow 0
		.amdhsa_exception_fp_ieee_underflow 0
		.amdhsa_exception_fp_ieee_inexact 0
		.amdhsa_exception_int_div_zero 0
	.end_amdhsa_kernel

; __global__ void __launch_bounds__(NWAVES * 64, 2) mk_fwd(Args args) {
amdhsa.kernels:
  - .agpr_count:     0
    .args:
      - .offset:         0
        .size:           888
        .value_kind:     by_value
      - .offset:         888
        .size:           4
        .value_kind:     hidden_block_count_x
      - .offset:         892
        .size:           4
        .value_kind:     hidden_block_count_y
      - .offset:         896
        .size:           4
        .value_kind:     hidden_block_count_z
      - .offset:         900
        .size:           2
        .value_kind:     hidden_group_size_x
      - .offset:         902
        .size:           2
        .value_kind:     hidden_group_size_y
      - .offset:         904
        .size:           2
        .value_kind:     hidden_group_size_z
      - .offset:         906
        .size:           2
        .value_kind:     hidden_remainder_x
      - .offset:         908
        .size:           2
        .value_kind:     hidden_remainder_y
      - .offset:         910
        .size:           2
        .value_kind:     hidden_remainder_z
      - .offset:         928
        .size:           8
        .value_kind:     hidden_global_offset_x
      - .offset:         936
        .size:           8
        .value_kind:     hidden_global_offset_y
      - .offset:         944
        .size:           8
        .value_kind:     hidden_global_offset_z
      - .offset:         952
        .size:           2
        .value_kind:     hidden_grid_dims
      - .offset:         1008
        .size:           4
        .value_kind:     hidden_dynamic_lds_size
    .group_segment_fixed_size: 0
    .kernarg_segment_align: 8
    .kernarg_segment_size: 1144
    .language:       OpenCL C
    .language_version:
      - 2
      - 0
    .max_flat_workgroup_size: 512
    .name:           _Z6mk_fwd4Args
    .private_segment_fixed_size: 0
    .sgpr_count:     108
    .sgpr_spill_count: 206
    .symbol:         _Z6mk_fwd4Args.kd
    .uniform_work_group_size: 1
    .uses_dynamic_stack: false
    .vgpr_count:     256
    .vgpr_spill_count: 0
    .wavefront_size: 64
